# v114 + LN panel-stats exchange: the acquire invalidate of wave 0 issued before its counter spin instead of after it
# baseline (speedup 1.0000x reference)
;     __device__ __forceinline__ bool run(const f32x4 (&v)[2][2][4][2], const Unit& u, int wr, int wc, int fr, int fq, LAS unsigned char* lds, int wid, int lane) const {
;     ...
;         if (wid == 0) {
;             bool dead = false; const unsigned long long t0 = __builtin_amdgcn_s_memrealtime(); const unsigned want = 8u * (unsigned)ntn;
;             for (;;) {
;                 if ((unsigned)__builtin_amdgcn_readfirstlane(__hip_atomic_load(cnt + 64 * u.pm, __ATOMIC_RELAXED, __HIP_MEMORY_SCOPE_AGENT)) >= want) break;
;                 if (__builtin_amdgcn_s_memrealtime() - t0 > 2000000ull) {
.LBB0_1462:
	s_or_b64 exec, exec, s[16:17]
	s_cmp_gt_u32 s34, 63
	s_cbranch_scc1 .LBB0_1479
	s_memrealtime s[16:17]
	s_lshl_b32 s18, s14, 6
	s_ashr_i32 s19, s18, 31
	s_lshl_b64 s[18:19], s[18:19], 2
	s_add_u32 s18, s13, s18
	s_addc_u32 s19, s15, s19
	buffer_inv sc1
	s_branch .LBB0_1466

;     __device__ __forceinline__ bool run(const f32x4 (&v)[2][2][4][2], const Unit& u, int wr, int wc, int fr, int fq, LAS unsigned char* lds, int wid, int lane) const {
;     ...
;                     dead = true; break; }
;                 __builtin_amdgcn_s_sleep(2);
;             }
;             __builtin_amdgcn_fence(__ATOMIC_ACQUIRE, "agent");
;             if (lane == 0) flag[0] = dead ? 1u : 0u;
.LBB0_1476:
	s_waitcnt vmcnt(0)
	s_and_b64 exec, exec, s[2:3]
	v_cndmask_b32_e64 v34, 0, 1, s[14:15]
	v_mov_b32_e32 v135, s33
	ds_write_b32 v135, v34 offset:10240

;     __device__ __forceinline__ bool run(const f32x4 (&v)[2][2][4][2], const Unit& u, int wr, int wc, int fr, int fq, LAS unsigned char* lds, int wid, int lane) const {
;     ...
;         if (wid == 0) {
;             bool dead = false; const unsigned long long t0 = __builtin_amdgcn_s_memrealtime(); const unsigned want = 8u * (unsigned)ntn;
;             for (;;) {
;                 if ((unsigned)__builtin_amdgcn_readfirstlane(__hip_atomic_load(cnt + 64 * u.pm, __ATOMIC_RELAXED, __HIP_MEMORY_SCOPE_AGENT)) >= want) break;
;                 if (__builtin_amdgcn_s_memrealtime() - t0 > 2000000ull) {
.LBB0_2278:
	s_or_b64 exec, exec, s[12:13]
	s_cmp_gt_u32 s26, 63
	s_cbranch_scc1 .LBB0_2295
	s_memrealtime s[12:13]
	s_lshl_b32 s14, s27, 6
	s_ashr_i32 s15, s14, 31
	s_lshl_b64 s[14:15], s[14:15], 2
	s_add_u32 s14, s16, s14
	s_addc_u32 s15, s17, s15
	buffer_inv sc1
	s_branch .LBB0_2282

;     __device__ __forceinline__ bool run(const f32x4 (&v)[2][2][4][2], const Unit& u, int wr, int wc, int fr, int fq, LAS unsigned char* lds, int wid, int lane) const {
;     ...
;                     dead = true; break; }
;                 __builtin_amdgcn_s_sleep(2);
;             }
;             __builtin_amdgcn_fence(__ATOMIC_ACQUIRE, "agent");
;             if (lane == 0) flag[0] = dead ? 1u : 0u;
.LBB0_2292:
	s_waitcnt vmcnt(0)
	s_and_b64 exec, exec, s[2:3]
	v_cndmask_b32_e64 v34, 0, 1, s[12:13]
	v_mov_b32_e32 v135, s24
	ds_write_b32 v135, v34 offset:10240
